# proj GEMM: rope-table loads hoisted out of serialized epilogue; LDS-DMA loads of k-tile pairs issued back to back (same 128B lines)
# speedup vs baseline: 1.0679x; 1.0171x over previous
.LBB0_124:
	v_mfma_f32_32x32x16_bf16 v[48:63], v[64:67], v[76:79], v[48:63]
	s_mov_b64 s[6:7], -1
	s_and_b64 vcc, exec, s[4:5]
	v_mfma_f32_32x32x16_bf16 v[32:47], v[64:67], v[80:83], v[32:47]
	v_mfma_f32_32x32x16_bf16 v[16:31], v[68:71], v[76:79], v[16:31]
	ds_read_b128 v[76:79], v136 offset:0x4000
	ds_read_b128 v[64:67], v136 offset:0x4800
	v_mfma_f32_32x32x16_bf16 v[0:15], v[68:71], v[80:83], v[0:15]
	v_mfma_f32_32x32x16_bf16 v[48:63], v[84:87], v[92:95], v[48:63]
	v_mfma_f32_32x32x16_bf16 v[32:47], v[84:87], v[88:91], v[32:47]
	ds_read_b128 v[84:87], v138 offset:0x4000
	v_mfma_f32_32x32x16_bf16 v[16:31], v[72:75], v[92:95], v[16:31]
	ds_read_b128 v[92:95], v138 offset:0x4800
	ds_read_b128 v[68:71], v137 offset:0x4000
	ds_read_b128 v[96:99], v137 offset:0x4800
	ds_read_b128 v[80:83], v139 offset:0x4000
	ds_read_b128 v[100:103], v139 offset:0x4800
	v_mfma_f32_32x32x16_bf16 v[0:15], v[72:75], v[88:91], v[0:15]
	s_waitcnt vmcnt(4)
.LBB0_132:
	s_waitcnt lgkmcnt(0)
	s_cmp_gt_u32 s1, 26
	s_cselect_b64 s[6:7], -1, 0
	s_and_b64 vcc, exec, s[6:7]
	s_barrier
	s_cbranch_vccnz .LBB0_134
	v_readfirstlane_b32 s2, v149
	v_readlane_b32 s48, v255, 57
	v_readlane_b32 s49, v255, 58
	v_add_u32_e32 v74, s0, v130
	v_add_u32_e32 v75, s0, v132
	v_add_u32_e32 v128, 0x80, v75
	s_add_u32 m0, s2, 0x0
	v_lshl_add_u64 v[72:73], v[128:129], 1, s[90:91]
	global_load_lds_dwordx4 v[72:73], off
	v_add_u32_e32 v128, 0x4480, v75
	s_add_u32 m0, s2, 0x400
	v_lshl_add_u64 v[72:73], v[128:129], 1, s[90:91]
	global_load_lds_dwordx4 v[72:73], off
	v_add_u32_e32 v128, 0x80, v74
	s_add_u32 m0, s2, 0x2000
	v_lshl_add_u64 v[72:73], v[128:129], 1, s[48:49]
	global_load_lds_dwordx4 v[72:73], off
	v_add_u32_e32 v128, 0x4480, v74
	s_add_u32 m0, s2, 0x2400
	v_lshl_add_u64 v[72:73], v[128:129], 1, s[48:49]
	global_load_lds_dwordx4 v[72:73], off
	v_add_u32_e32 v128, 0xa0, v75
	s_add_u32 m0, s2, 0x4000
	v_lshl_add_u64 v[72:73], v[128:129], 1, s[90:91]
	global_load_lds_dwordx4 v[72:73], off
	v_add_u32_e32 v128, 0x44a0, v75
	s_add_u32 m0, s2, 0x4400
	v_lshl_add_u64 v[72:73], v[128:129], 1, s[90:91]
	global_load_lds_dwordx4 v[72:73], off
	v_add_u32_e32 v128, 0xa0, v74
	s_add_u32 m0, s2, 0x6000
	v_lshl_add_u64 v[72:73], v[128:129], 1, s[48:49]
	global_load_lds_dwordx4 v[72:73], off
	v_add_u32_e32 v128, 0x44a0, v74
	s_add_u32 m0, s2, 0x6400
	v_lshl_add_u64 v[72:73], v[128:129], 1, s[48:49]
	global_load_lds_dwordx4 v[72:73], off

.LBB0_138:
	s_waitcnt lgkmcnt(0)
	s_cmp_gt_u32 s1, 25
	s_cselect_b64 s[6:7], -1, 0
	s_and_b64 vcc, exec, s[6:7]
	s_barrier
	s_cbranch_vccnz .LBB0_140
.LBB0_140:
	v_mfma_f32_32x32x16_bf16 v[48:63], v[64:67], v[76:79], v[48:63]
	s_mov_b64 s[28:29], -1
	s_and_b64 vcc, exec, s[4:5]
	ds_read_b128 v[116:119], v136 offset:0xc000
	ds_read_b128 v[104:107], v136 offset:0xc800
	ds_read_b128 v[120:123], v138 offset:0xc000
	ds_read_b128 v[124:127], v138 offset:0xc800
	ds_read_b128 v[108:111], v137 offset:0xc000
	v_mfma_f32_32x32x16_bf16 v[32:47], v[64:67], v[80:83], v[32:47]
	ds_read_b128 v[96:99], v137 offset:0xc800
	ds_read_b128 v[112:115], v139 offset:0xc000
	ds_read_b128 v[100:103], v139 offset:0xc800
	v_mfma_f32_32x32x16_bf16 v[16:31], v[68:71], v[76:79], v[16:31]
	v_mfma_f32_32x32x16_bf16 v[0:15], v[68:71], v[80:83], v[0:15]
	v_mfma_f32_32x32x16_bf16 v[48:63], v[84:87], v[92:95], v[48:63]
	v_mfma_f32_32x32x16_bf16 v[32:47], v[84:87], v[88:91], v[32:47]
	v_mfma_f32_32x32x16_bf16 v[16:31], v[72:75], v[92:95], v[16:31]
	v_mfma_f32_32x32x16_bf16 v[0:15], v[72:75], v[88:91], v[0:15]
	s_cbranch_vccz .LBB0_142
	s_waitcnt lgkmcnt(0)
	s_mov_b64 s[28:29], 0
.LBB0_142:
	s_andn2_b64 vcc, exec, s[28:29]
	s_cbranch_vccnz .LBB0_121
	s_waitcnt vmcnt(4)
.LBB0_147:
	s_waitcnt lgkmcnt(0)
	s_cmp_gt_u32 s1, 24
	s_barrier
	s_cbranch_scc1 .LBB0_120
	v_readfirstlane_b32 s2, v149
	v_readlane_b32 s48, v255, 57
	v_readlane_b32 s49, v255, 58
	v_add_u32_e32 v66, s0, v130
	v_add_u32_e32 v67, s0, v132
	v_add_u32_e32 v128, 0xc0, v67
	s_add_u32 m0, s2, 0x8000
	v_lshl_add_u64 v[64:65], v[128:129], 1, s[90:91]
	global_load_lds_dwordx4 v[64:65], off
	v_add_u32_e32 v128, 0x44c0, v67
	s_add_u32 m0, s2, 0x8400
	v_lshl_add_u64 v[64:65], v[128:129], 1, s[90:91]
	global_load_lds_dwordx4 v[64:65], off
	v_add_u32_e32 v128, 0xc0, v66
	s_add_u32 m0, s2, 0xa000
	v_lshl_add_u64 v[64:65], v[128:129], 1, s[48:49]
	global_load_lds_dwordx4 v[64:65], off
	v_add_u32_e32 v128, 0x44c0, v66
	s_add_u32 m0, s2, 0xa400
	v_lshl_add_u64 v[64:65], v[128:129], 1, s[48:49]
	global_load_lds_dwordx4 v[64:65], off
	v_add_u32_e32 v128, 0xe0, v67
	s_add_u32 m0, s2, 0xc000
	v_lshl_add_u64 v[64:65], v[128:129], 1, s[90:91]
	global_load_lds_dwordx4 v[64:65], off
	v_add_u32_e32 v128, 0x44e0, v67
	s_add_u32 m0, s2, 0xc400
	v_lshl_add_u64 v[64:65], v[128:129], 1, s[90:91]
	global_load_lds_dwordx4 v[64:65], off
	v_add_u32_e32 v128, 0xe0, v66
	s_add_u32 m0, s2, 0xe000
	v_lshl_add_u64 v[64:65], v[128:129], 1, s[48:49]
	global_load_lds_dwordx4 v[64:65], off
	v_add_u32_e32 v128, 0x44e0, v66
	s_add_u32 m0, s2, 0xe400
	v_lshl_add_u64 v[64:65], v[128:129], 1, s[48:49]
	global_load_lds_dwordx4 v[64:65], off
	s_branch .LBB0_120

.LBB0_174:
	v_readlane_b32 s36, v255, 4
	v_readlane_b32 s37, v255, 5
	v_add_lshl_u32 v75, v68, s55, 3
	v_and_b32_e32 v74, 7, v67
	s_movk_i32 s0, 0x3ff8
	v_and_or_b32 v75, v75, s0, v74
	v_lshlrev_b32_e32 v75, 3, v75
	s_nop 1
	global_load_dwordx2 v[76:77], v75, s[36:37] offset:0
	global_load_dwordx2 v[78:79], v75, s[36:37] offset:64
	global_load_dwordx2 v[80:81], v75, s[36:37] offset:128
	global_load_dwordx2 v[82:83], v75, s[36:37] offset:192
	global_load_dwordx2 v[84:85], v75, s[36:37] offset:512
	global_load_dwordx2 v[86:87], v75, s[36:37] offset:576
	global_load_dwordx2 v[88:89], v75, s[36:37] offset:640
	global_load_dwordx2 v[90:91], v75, s[36:37] offset:704
	global_load_dwordx2 v[92:93], v75, s[36:37] offset:1024
	global_load_dwordx2 v[94:95], v75, s[36:37] offset:1088
	global_load_dwordx2 v[96:97], v75, s[36:37] offset:1152
	global_load_dwordx2 v[98:99], v75, s[36:37] offset:1216
	global_load_dwordx2 v[100:101], v75, s[36:37] offset:1536
	global_load_dwordx2 v[102:103], v75, s[36:37] offset:1600
	global_load_dwordx2 v[104:105], v75, s[36:37] offset:1664
	global_load_dwordx2 v[106:107], v75, s[36:37] offset:1728
	global_load_dwordx2 v[108:109], v75, s[36:37] offset:2048
	global_load_dwordx2 v[110:111], v75, s[36:37] offset:2112
	global_load_dwordx2 v[112:113], v75, s[36:37] offset:2176
	global_load_dwordx2 v[114:115], v75, s[36:37] offset:2240
	global_load_dwordx2 v[116:117], v75, s[36:37] offset:2560
	global_load_dwordx2 v[118:119], v75, s[36:37] offset:2624
	global_load_dwordx2 v[120:121], v75, s[36:37] offset:2688
	global_load_dwordx2 v[122:123], v75, s[36:37] offset:2752
	global_load_dwordx2 v[124:125], v75, s[36:37] offset:3072
	global_load_dwordx2 v[126:127], v75, s[36:37] offset:3136
	v_and_b32_e32 v70, 64, v205
	v_xor_b32_e32 v69, 8, v205
	v_add_u32_e32 v70, 64, v70
	v_cmp_lt_i32_e32 vcc, v69, v70
	s_nop 1
	v_cndmask_b32_e32 v69, v205, v69, vcc
	v_lshlrev_b32_e32 v70, 2, v69
	ds_bpermute_b32 v71, v70, v48
	v_cmp_gt_u32_e32 vcc, 16, v67
	v_and_b32_e32 v69, 7, v66
	s_and_saveexec_b64 s[6:7], vcc
	s_cbranch_execz .LBB0_176
	s_movk_i32 s0, 0x3e20
	v_readlane_b32 s36, v255, 4
	v_readlane_b32 s37, v255, 5
	v_cmp_gt_u32_e64 s[4:5], 8, v67
	v_readlane_b32 s38, v255, 6
	v_readlane_b32 s39, v255, 7
	v_readlane_b32 s40, v255, 8
	v_readlane_b32 s41, v255, 9
	v_readlane_b32 s42, v255, 10
	v_readlane_b32 s43, v255, 11
	s_waitcnt vmcnt(0) lgkmcnt(0)
	v_mul_f32_e32 v71, v77, v71
	v_cndmask_b32_e64 v71, v71, -v71, s[4:5]
	v_fmac_f32_e32 v71, v48, v76
	v_mov_b32_e32 v48, v71
.LBB0_176:
	s_or_b64 exec, exec, s[6:7]
	ds_bpermute_b32 v72, v70, v49
	v_cvt_pk_bf16_f32 v48, v48, s0
	s_waitcnt lgkmcnt(0)
	v_mad_u32_u24 v71, v68, s58, v65
	ds_write_b16 v71, v48
	v_add_u32_e32 v48, s55, v68
	s_and_saveexec_b64 s[6:7], vcc
	s_cbranch_execz .LBB0_178
	v_readlane_b32 s36, v255, 4
	v_readlane_b32 s37, v255, 5
	v_cmp_gt_u32_e64 s[4:5], 8, v67
	v_readlane_b32 s38, v255, 6
	v_readlane_b32 s39, v255, 7
	v_readlane_b32 s40, v255, 8
	v_readlane_b32 s41, v255, 9
	v_readlane_b32 s42, v255, 10
	v_readlane_b32 s43, v255, 11
	s_waitcnt vmcnt(0)
	v_mul_f32_e32 v72, v79, v72
	v_cndmask_b32_e64 v72, v72, -v72, s[4:5]
	v_fmac_f32_e32 v72, v49, v78
	v_mov_b32_e32 v49, v72
.LBB0_178:
	s_or_b64 exec, exec, s[6:7]
	v_mul_u32_u24_e32 v72, 0x110, v68
	v_add_u32_e32 v72, 0x110, v72
	v_cvt_pk_bf16_f32 v73, v49, s0
	v_lshl_add_u32 v49, v64, 1, v72
	ds_write_b16 v49, v73
	ds_bpermute_b32 v73, v70, v50
	s_and_saveexec_b64 s[6:7], vcc
	s_cbranch_execz .LBB0_180
	v_readlane_b32 s36, v255, 4
	v_readlane_b32 s37, v255, 5
	v_cmp_gt_u32_e64 s[4:5], 8, v67
	v_readlane_b32 s38, v255, 6
	v_readlane_b32 s39, v255, 7
	v_readlane_b32 s40, v255, 8
	v_readlane_b32 s41, v255, 9
	v_readlane_b32 s42, v255, 10
	v_readlane_b32 s43, v255, 11
	s_waitcnt vmcnt(0) lgkmcnt(0)
	v_mul_f32_e32 v73, v81, v73
	v_cndmask_b32_e64 v73, v73, -v73, s[4:5]
	v_fmac_f32_e32 v73, v50, v80
	v_mov_b32_e32 v50, v73
.LBB0_180:
	s_or_b64 exec, exec, s[6:7]
	v_add_u32_e32 v72, 0x110, v72
	s_waitcnt lgkmcnt(0)
	v_cvt_pk_bf16_f32 v73, v50, s0
	v_lshl_add_u32 v50, v64, 1, v72
	ds_write_b16 v50, v73
	ds_bpermute_b32 v73, v70, v51
	s_and_saveexec_b64 s[6:7], vcc
	s_cbranch_execz .LBB0_182
	v_readlane_b32 s36, v255, 4
	v_readlane_b32 s37, v255, 5
	v_cmp_gt_u32_e64 s[4:5], 8, v67
	v_readlane_b32 s38, v255, 6
	v_readlane_b32 s39, v255, 7
	v_readlane_b32 s40, v255, 8
	v_readlane_b32 s41, v255, 9
	v_readlane_b32 s42, v255, 10
	v_readlane_b32 s43, v255, 11
	s_waitcnt vmcnt(0) lgkmcnt(0)
	v_mul_f32_e32 v73, v83, v73
	v_cndmask_b32_e64 v73, v73, -v73, s[4:5]
	v_fmac_f32_e32 v73, v51, v82
	v_mov_b32_e32 v51, v73
.LBB0_182:
	s_or_b64 exec, exec, s[6:7]
	v_add_u32_e32 v72, 0x110, v72
	s_waitcnt lgkmcnt(0)
	v_cvt_pk_bf16_f32 v73, v51, s0
	v_lshl_add_u32 v51, v64, 1, v72
	ds_write_b16 v51, v73
	ds_bpermute_b32 v73, v70, v52
	s_and_saveexec_b64 s[6:7], vcc
	s_cbranch_execz .LBB0_184
	v_readlane_b32 s36, v255, 4
	v_readlane_b32 s37, v255, 5
	v_cmp_gt_u32_e64 s[4:5], 8, v67
	v_readlane_b32 s38, v255, 6
	v_readlane_b32 s39, v255, 7
	v_readlane_b32 s40, v255, 8
	v_readlane_b32 s41, v255, 9
	v_readlane_b32 s42, v255, 10
	v_readlane_b32 s43, v255, 11
	s_waitcnt vmcnt(0) lgkmcnt(0)
	v_mul_f32_e32 v73, v85, v73
	v_cndmask_b32_e64 v73, v73, -v73, s[4:5]
	v_fmac_f32_e32 v73, v52, v84
	v_mov_b32_e32 v52, v73
.LBB0_184:
	s_or_b64 exec, exec, s[6:7]
	v_add_u32_e32 v72, 0x550, v72
	s_waitcnt lgkmcnt(0)
	v_cvt_pk_bf16_f32 v73, v52, s0
	v_lshl_add_u32 v52, v64, 1, v72
	ds_write_b16 v52, v73
	ds_bpermute_b32 v73, v70, v53
	s_and_saveexec_b64 s[6:7], vcc
	s_cbranch_execz .LBB0_186
	v_readlane_b32 s36, v255, 4
	v_readlane_b32 s37, v255, 5
	v_cmp_gt_u32_e64 s[4:5], 8, v67
	v_readlane_b32 s38, v255, 6
	v_readlane_b32 s39, v255, 7
	v_readlane_b32 s40, v255, 8
	v_readlane_b32 s41, v255, 9
	v_readlane_b32 s42, v255, 10
	v_readlane_b32 s43, v255, 11
	s_waitcnt vmcnt(0) lgkmcnt(0)
	v_mul_f32_e32 v73, v87, v73
	v_cndmask_b32_e64 v73, v73, -v73, s[4:5]
	v_fmac_f32_e32 v73, v53, v86
	v_mov_b32_e32 v53, v73
.LBB0_186:
	s_or_b64 exec, exec, s[6:7]
	global_load_dwordx2 v[76:77], v75, s[36:37] offset:3200
	global_load_dwordx2 v[78:79], v75, s[36:37] offset:3264
	global_load_dwordx2 v[80:81], v75, s[36:37] offset:3584
	global_load_dwordx2 v[82:83], v75, s[36:37] offset:3648
	global_load_dwordx2 v[84:85], v75, s[36:37] offset:3712
	global_load_dwordx2 v[86:87], v75, s[36:37] offset:3776
	v_add_u32_e32 v72, 0x110, v72
	s_waitcnt lgkmcnt(0)
	v_cvt_pk_bf16_f32 v73, v53, s0
	v_lshl_add_u32 v53, v64, 1, v72
	ds_write_b16 v53, v73
	ds_bpermute_b32 v73, v70, v54
	s_and_saveexec_b64 s[6:7], vcc
	s_cbranch_execz .LBB0_188
	v_readlane_b32 s36, v255, 4
	v_readlane_b32 s37, v255, 5
	v_cmp_gt_u32_e64 s[4:5], 8, v67
	v_readlane_b32 s38, v255, 6
	v_readlane_b32 s39, v255, 7
	v_readlane_b32 s40, v255, 8
	v_readlane_b32 s41, v255, 9
	v_readlane_b32 s42, v255, 10
	v_readlane_b32 s43, v255, 11
	s_waitcnt lgkmcnt(0)
	v_mul_f32_e32 v73, v89, v73
	v_cndmask_b32_e64 v73, v73, -v73, s[4:5]
	v_fmac_f32_e32 v73, v54, v88
	v_mov_b32_e32 v54, v73
.LBB0_188:
	s_or_b64 exec, exec, s[6:7]
	v_add_u32_e32 v72, 0x110, v72
	s_waitcnt lgkmcnt(0)
	v_cvt_pk_bf16_f32 v73, v54, s0
	v_lshl_add_u32 v54, v64, 1, v72
	ds_write_b16 v54, v73
	ds_bpermute_b32 v73, v70, v55
	s_and_saveexec_b64 s[6:7], vcc
	s_cbranch_execz .LBB0_190
	v_readlane_b32 s36, v255, 4
	v_readlane_b32 s37, v255, 5
	v_cmp_gt_u32_e64 s[4:5], 8, v67
	v_readlane_b32 s38, v255, 6
	v_readlane_b32 s39, v255, 7
	v_readlane_b32 s40, v255, 8
	v_readlane_b32 s41, v255, 9
	v_readlane_b32 s42, v255, 10
	v_readlane_b32 s43, v255, 11
	s_waitcnt lgkmcnt(0)
	v_mul_f32_e32 v73, v91, v73
	v_cndmask_b32_e64 v73, v73, -v73, s[4:5]
	v_fmac_f32_e32 v73, v55, v90
	v_mov_b32_e32 v55, v73
.LBB0_190:
	s_or_b64 exec, exec, s[6:7]
	v_add_u32_e32 v72, 0x110, v72
	s_waitcnt lgkmcnt(0)
	v_cvt_pk_bf16_f32 v73, v55, s0
	v_lshl_add_u32 v55, v64, 1, v72
	ds_write_b16 v55, v73
	ds_bpermute_b32 v73, v70, v56
	s_and_saveexec_b64 s[6:7], vcc
	s_cbranch_execz .LBB0_192
	v_readlane_b32 s36, v255, 4
	v_readlane_b32 s37, v255, 5
	v_cmp_gt_u32_e64 s[4:5], 8, v67
	v_readlane_b32 s38, v255, 6
	v_readlane_b32 s39, v255, 7
	v_readlane_b32 s40, v255, 8
	v_readlane_b32 s41, v255, 9
	v_readlane_b32 s42, v255, 10
	v_readlane_b32 s43, v255, 11
	s_waitcnt lgkmcnt(0)
	v_mul_f32_e32 v73, v93, v73
	v_cndmask_b32_e64 v73, v73, -v73, s[4:5]
	v_fmac_f32_e32 v73, v56, v92
	v_mov_b32_e32 v56, v73
.LBB0_192:
	s_or_b64 exec, exec, s[6:7]
	v_add_u32_e32 v72, 0x550, v72
	s_waitcnt lgkmcnt(0)
	v_cvt_pk_bf16_f32 v73, v56, s0
	v_lshl_add_u32 v56, v64, 1, v72
	ds_write_b16 v56, v73
	ds_bpermute_b32 v73, v70, v57
	s_and_saveexec_b64 s[6:7], vcc
	s_cbranch_execz .LBB0_194
	v_readlane_b32 s36, v255, 4
	v_readlane_b32 s37, v255, 5
	v_cmp_gt_u32_e64 s[4:5], 8, v67
	v_readlane_b32 s38, v255, 6
	v_readlane_b32 s39, v255, 7
	v_readlane_b32 s40, v255, 8
	v_readlane_b32 s41, v255, 9
	v_readlane_b32 s42, v255, 10
	v_readlane_b32 s43, v255, 11
	s_waitcnt lgkmcnt(0)
	v_mul_f32_e32 v73, v95, v73
	v_cndmask_b32_e64 v73, v73, -v73, s[4:5]
	v_fmac_f32_e32 v73, v57, v94
	v_mov_b32_e32 v57, v73
.LBB0_194:
	s_or_b64 exec, exec, s[6:7]
	v_add_u32_e32 v72, 0x110, v72
	s_waitcnt lgkmcnt(0)
	v_cvt_pk_bf16_f32 v73, v57, s0
	v_lshl_add_u32 v57, v64, 1, v72
	ds_write_b16 v57, v73
	ds_bpermute_b32 v73, v70, v58
	s_and_saveexec_b64 s[6:7], vcc
	s_cbranch_execz .LBB0_196
	v_readlane_b32 s36, v255, 4
	v_readlane_b32 s37, v255, 5
	v_cmp_gt_u32_e64 s[4:5], 8, v67
	v_readlane_b32 s38, v255, 6
	v_readlane_b32 s39, v255, 7
	v_readlane_b32 s40, v255, 8
	v_readlane_b32 s41, v255, 9
	v_readlane_b32 s42, v255, 10
	v_readlane_b32 s43, v255, 11
	s_waitcnt lgkmcnt(0)
	v_mul_f32_e32 v73, v97, v73
	v_cndmask_b32_e64 v73, v73, -v73, s[4:5]
	v_fmac_f32_e32 v73, v58, v96
	v_mov_b32_e32 v58, v73
.LBB0_196:
	s_or_b64 exec, exec, s[6:7]
	v_add_u32_e32 v72, 0x110, v72
	s_waitcnt lgkmcnt(0)
	v_cvt_pk_bf16_f32 v73, v58, s0
	v_lshl_add_u32 v58, v64, 1, v72
	ds_write_b16 v58, v73
	ds_bpermute_b32 v73, v70, v59
	s_and_saveexec_b64 s[6:7], vcc
	s_cbranch_execz .LBB0_198
	v_readlane_b32 s36, v255, 4
	v_readlane_b32 s37, v255, 5
	v_cmp_gt_u32_e64 s[4:5], 8, v67
	v_readlane_b32 s38, v255, 6
	v_readlane_b32 s39, v255, 7
	v_readlane_b32 s40, v255, 8
	v_readlane_b32 s41, v255, 9
	v_readlane_b32 s42, v255, 10
	v_readlane_b32 s43, v255, 11
	s_waitcnt lgkmcnt(0)
	v_mul_f32_e32 v73, v99, v73
	v_cndmask_b32_e64 v73, v73, -v73, s[4:5]
	v_fmac_f32_e32 v73, v59, v98
	v_mov_b32_e32 v59, v73
.LBB0_198:
	s_or_b64 exec, exec, s[6:7]
	v_add_u32_e32 v72, 0x110, v72
	s_waitcnt lgkmcnt(0)
	v_cvt_pk_bf16_f32 v73, v59, s0
	v_lshl_add_u32 v59, v64, 1, v72
	ds_write_b16 v59, v73
	ds_bpermute_b32 v73, v70, v60
	s_and_saveexec_b64 s[6:7], vcc
	s_cbranch_execz .LBB0_200
	v_readlane_b32 s36, v255, 4
	v_readlane_b32 s37, v255, 5
	v_cmp_gt_u32_e64 s[4:5], 8, v67
	v_readlane_b32 s38, v255, 6
	v_readlane_b32 s39, v255, 7
	v_readlane_b32 s40, v255, 8
	v_readlane_b32 s41, v255, 9
	v_readlane_b32 s42, v255, 10
	v_readlane_b32 s43, v255, 11
	s_waitcnt lgkmcnt(0)
	v_mul_f32_e32 v73, v101, v73
	v_cndmask_b32_e64 v73, v73, -v73, s[4:5]
	v_fmac_f32_e32 v73, v60, v100
	v_mov_b32_e32 v60, v73
.LBB0_200:
	s_or_b64 exec, exec, s[6:7]
	v_add_u32_e32 v72, 0x550, v72
	s_waitcnt lgkmcnt(0)
	v_cvt_pk_bf16_f32 v73, v60, s0
	v_lshl_add_u32 v60, v64, 1, v72
	ds_write_b16 v60, v73
	ds_bpermute_b32 v73, v70, v61
	s_and_saveexec_b64 s[6:7], vcc
	s_cbranch_execz .LBB0_202
	v_readlane_b32 s36, v255, 4
	v_readlane_b32 s37, v255, 5
	v_cmp_gt_u32_e64 s[4:5], 8, v67
	v_readlane_b32 s38, v255, 6
	v_readlane_b32 s39, v255, 7
	v_readlane_b32 s40, v255, 8
	v_readlane_b32 s41, v255, 9
	v_readlane_b32 s42, v255, 10
	v_readlane_b32 s43, v255, 11
	s_waitcnt lgkmcnt(0)
	v_mul_f32_e32 v73, v103, v73
	v_cndmask_b32_e64 v73, v73, -v73, s[4:5]
	v_fmac_f32_e32 v73, v61, v102
	v_mov_b32_e32 v61, v73
.LBB0_202:
	s_or_b64 exec, exec, s[6:7]
	v_add_u32_e32 v72, 0x110, v72
	s_waitcnt lgkmcnt(0)
	v_cvt_pk_bf16_f32 v73, v61, s0
	v_lshl_add_u32 v61, v64, 1, v72
	ds_write_b16 v61, v73
	ds_bpermute_b32 v73, v70, v62
	s_and_saveexec_b64 s[6:7], vcc
	s_cbranch_execz .LBB0_204
	v_readlane_b32 s36, v255, 4
	v_readlane_b32 s37, v255, 5
	v_cmp_gt_u32_e64 s[4:5], 8, v67
	v_readlane_b32 s38, v255, 6
	v_readlane_b32 s39, v255, 7
	v_readlane_b32 s40, v255, 8
	v_readlane_b32 s41, v255, 9
	v_readlane_b32 s42, v255, 10
	v_readlane_b32 s43, v255, 11
	s_waitcnt lgkmcnt(0)
	v_mul_f32_e32 v73, v105, v73
	v_cndmask_b32_e64 v73, v73, -v73, s[4:5]
	v_fmac_f32_e32 v73, v62, v104
	v_mov_b32_e32 v62, v73
.LBB0_204:
	s_or_b64 exec, exec, s[6:7]
	v_add_u32_e32 v72, 0x110, v72
	s_waitcnt lgkmcnt(0)
	v_cvt_pk_bf16_f32 v73, v62, s0
	v_lshl_add_u32 v62, v64, 1, v72
	ds_write_b16 v62, v73
	ds_bpermute_b32 v73, v70, v63
	s_and_saveexec_b64 s[6:7], vcc
	s_cbranch_execz .LBB0_206
	v_readlane_b32 s36, v255, 4
	v_readlane_b32 s37, v255, 5
	v_cmp_gt_u32_e64 s[4:5], 8, v67
	v_readlane_b32 s38, v255, 6
	v_readlane_b32 s39, v255, 7
	v_readlane_b32 s40, v255, 8
	v_readlane_b32 s41, v255, 9
	v_readlane_b32 s42, v255, 10
	v_readlane_b32 s43, v255, 11
	s_waitcnt lgkmcnt(0)
	v_mul_f32_e32 v73, v107, v73
	v_cndmask_b32_e64 v73, v73, -v73, s[4:5]
	v_fmac_f32_e32 v73, v63, v106
	v_mov_b32_e32 v63, v73
.LBB0_206:
	s_or_b64 exec, exec, s[6:7]
	s_waitcnt lgkmcnt(0)
	v_cvt_pk_bf16_f32 v73, v63, s0
	v_add_u32_e32 v63, 0x110, v72
	v_lshl_add_u32 v72, v64, 1, v63
	v_cvt_pk_bf16_f32 v32, v32, s0
	ds_write_b16 v72, v73
	ds_write_b16 v71, v32 offset:64
	v_cvt_pk_bf16_f32 v32, v33, s0
	ds_write_b16 v49, v32 offset:64
	v_cvt_pk_bf16_f32 v32, v34, s0
	ds_write_b16 v50, v32 offset:64
	v_cvt_pk_bf16_f32 v32, v35, s0
	ds_write_b16 v51, v32 offset:64
	v_cvt_pk_bf16_f32 v32, v36, s0
	ds_write_b16 v52, v32 offset:64
	v_cvt_pk_bf16_f32 v32, v37, s0
	ds_write_b16 v53, v32 offset:64
	v_cvt_pk_bf16_f32 v32, v38, s0
	ds_write_b16 v54, v32 offset:64
	v_cvt_pk_bf16_f32 v32, v39, s0
	ds_write_b16 v55, v32 offset:64
	v_cvt_pk_bf16_f32 v32, v40, s0
	ds_write_b16 v56, v32 offset:64
	v_cvt_pk_bf16_f32 v32, v41, s0
	ds_write_b16 v57, v32 offset:64
	v_cvt_pk_bf16_f32 v32, v42, s0
	ds_write_b16 v58, v32 offset:64
	v_cvt_pk_bf16_f32 v32, v43, s0
	ds_write_b16 v59, v32 offset:64
	v_cvt_pk_bf16_f32 v32, v44, s0
	ds_write_b16 v60, v32 offset:64
	v_cvt_pk_bf16_f32 v32, v45, s0
	ds_write_b16 v61, v32 offset:64
	ds_bpermute_b32 v32, v70, v16
	v_cvt_pk_bf16_f32 v33, v46, s0
	ds_write_b16 v62, v33 offset:64
	v_cvt_pk_bf16_f32 v33, v47, s0
	ds_write_b16 v72, v33 offset:64
	s_and_saveexec_b64 s[6:7], vcc
	s_cbranch_execz .LBB0_208
	v_readlane_b32 s36, v255, 4
	v_readlane_b32 s37, v255, 5
	v_cmp_gt_u32_e64 s[4:5], 8, v67
	v_readlane_b32 s38, v255, 6
	v_readlane_b32 s39, v255, 7
	v_readlane_b32 s40, v255, 8
	v_readlane_b32 s41, v255, 9
	v_readlane_b32 s42, v255, 10
	v_readlane_b32 s43, v255, 11
	s_waitcnt lgkmcnt(0)
	v_mul_f32_e32 v32, v109, v32
	v_cndmask_b32_e64 v32, v32, -v32, s[4:5]
	v_fmac_f32_e32 v32, v16, v108
	v_mov_b32_e32 v16, v32
.LBB0_208:
	s_or_b64 exec, exec, s[6:7]
	s_waitcnt lgkmcnt(0)
	v_add_u32_e32 v32, 0x550, v63
	v_cvt_pk_bf16_f32 v33, v16, s0
	v_lshl_add_u32 v16, v64, 1, v32
	ds_write_b16 v16, v33
	ds_bpermute_b32 v33, v70, v17
	s_and_saveexec_b64 s[6:7], vcc
	s_cbranch_execz .LBB0_210
	v_readlane_b32 s36, v255, 4
	v_readlane_b32 s37, v255, 5
	v_cmp_gt_u32_e64 s[4:5], 8, v67
	v_readlane_b32 s38, v255, 6
	v_readlane_b32 s39, v255, 7
	v_readlane_b32 s40, v255, 8
	v_readlane_b32 s41, v255, 9
	v_readlane_b32 s42, v255, 10
	v_readlane_b32 s43, v255, 11
	s_waitcnt lgkmcnt(0)
	v_mul_f32_e32 v33, v111, v33
	v_cndmask_b32_e64 v33, v33, -v33, s[4:5]
	v_fmac_f32_e32 v33, v17, v110
	v_mov_b32_e32 v17, v33
.LBB0_210:
	s_or_b64 exec, exec, s[6:7]
	v_add_u32_e32 v32, 0x110, v32
	s_waitcnt lgkmcnt(0)
	v_cvt_pk_bf16_f32 v33, v17, s0
	v_lshl_add_u32 v17, v64, 1, v32
	ds_write_b16 v17, v33
	ds_bpermute_b32 v33, v70, v18
	s_and_saveexec_b64 s[6:7], vcc
	s_cbranch_execz .LBB0_212
	v_readlane_b32 s36, v255, 4
	v_readlane_b32 s37, v255, 5
	v_cmp_gt_u32_e64 s[4:5], 8, v67
	v_readlane_b32 s38, v255, 6
	v_readlane_b32 s39, v255, 7
	v_readlane_b32 s40, v255, 8
	v_readlane_b32 s41, v255, 9
	v_readlane_b32 s42, v255, 10
	v_readlane_b32 s43, v255, 11
	s_waitcnt lgkmcnt(0)
	v_mul_f32_e32 v33, v113, v33
	v_cndmask_b32_e64 v33, v33, -v33, s[4:5]
	v_fmac_f32_e32 v33, v18, v112
	v_mov_b32_e32 v18, v33
.LBB0_212:
	s_or_b64 exec, exec, s[6:7]
	v_add_u32_e32 v32, 0x110, v32
	s_waitcnt lgkmcnt(0)
	v_cvt_pk_bf16_f32 v33, v18, s0
	v_lshl_add_u32 v18, v64, 1, v32
	ds_write_b16 v18, v33
	ds_bpermute_b32 v33, v70, v19
	s_and_saveexec_b64 s[6:7], vcc
	s_cbranch_execz .LBB0_214
	v_readlane_b32 s36, v255, 4
	v_readlane_b32 s37, v255, 5
	v_cmp_gt_u32_e64 s[4:5], 8, v67
	v_readlane_b32 s38, v255, 6
	v_readlane_b32 s39, v255, 7
	v_readlane_b32 s40, v255, 8
	v_readlane_b32 s41, v255, 9
	v_readlane_b32 s42, v255, 10
	v_readlane_b32 s43, v255, 11
	s_waitcnt lgkmcnt(0)
	v_mul_f32_e32 v33, v115, v33
	v_cndmask_b32_e64 v33, v33, -v33, s[4:5]
	v_fmac_f32_e32 v33, v19, v114
	v_mov_b32_e32 v19, v33
.LBB0_214:
	s_or_b64 exec, exec, s[6:7]
	v_add_u32_e32 v32, 0x110, v32
	s_waitcnt lgkmcnt(0)
	v_cvt_pk_bf16_f32 v33, v19, s0
	v_lshl_add_u32 v19, v64, 1, v32
	ds_write_b16 v19, v33
	ds_bpermute_b32 v33, v70, v20
	s_and_saveexec_b64 s[6:7], vcc
	s_cbranch_execz .LBB0_216
	v_readlane_b32 s36, v255, 4
	v_readlane_b32 s37, v255, 5
	v_cmp_gt_u32_e64 s[4:5], 8, v67
	v_readlane_b32 s38, v255, 6
	v_readlane_b32 s39, v255, 7
	v_readlane_b32 s40, v255, 8
	v_readlane_b32 s41, v255, 9
	v_readlane_b32 s42, v255, 10
	v_readlane_b32 s43, v255, 11
	s_waitcnt lgkmcnt(0)
	v_mul_f32_e32 v33, v117, v33
	v_cndmask_b32_e64 v33, v33, -v33, s[4:5]
	v_fmac_f32_e32 v33, v20, v116
	v_mov_b32_e32 v20, v33
.LBB0_216:
	s_or_b64 exec, exec, s[6:7]
	v_add_u32_e32 v32, 0x550, v32
	s_waitcnt lgkmcnt(0)
	v_cvt_pk_bf16_f32 v33, v20, s0
	v_lshl_add_u32 v20, v64, 1, v32
	ds_write_b16 v20, v33
	ds_bpermute_b32 v33, v70, v21
	s_and_saveexec_b64 s[6:7], vcc
	s_cbranch_execz .LBB0_218
	v_readlane_b32 s36, v255, 4
	v_readlane_b32 s37, v255, 5
	v_cmp_gt_u32_e64 s[4:5], 8, v67
	v_readlane_b32 s38, v255, 6
	v_readlane_b32 s39, v255, 7
	v_readlane_b32 s40, v255, 8
	v_readlane_b32 s41, v255, 9
	v_readlane_b32 s42, v255, 10
	v_readlane_b32 s43, v255, 11
	s_waitcnt lgkmcnt(0)
	v_mul_f32_e32 v33, v119, v33
	v_cndmask_b32_e64 v33, v33, -v33, s[4:5]
	v_fmac_f32_e32 v33, v21, v118
	v_mov_b32_e32 v21, v33
.LBB0_218:
	s_or_b64 exec, exec, s[6:7]
	v_add_u32_e32 v32, 0x110, v32
	s_waitcnt lgkmcnt(0)
	v_cvt_pk_bf16_f32 v33, v21, s0
	v_lshl_add_u32 v21, v64, 1, v32
	ds_write_b16 v21, v33
	ds_bpermute_b32 v33, v70, v22
	s_and_saveexec_b64 s[6:7], vcc
	s_cbranch_execz .LBB0_220
	v_readlane_b32 s36, v255, 4
	v_readlane_b32 s37, v255, 5
	v_cmp_gt_u32_e64 s[4:5], 8, v67
	v_readlane_b32 s38, v255, 6
	v_readlane_b32 s39, v255, 7
	v_readlane_b32 s40, v255, 8
	v_readlane_b32 s41, v255, 9
	v_readlane_b32 s42, v255, 10
	v_readlane_b32 s43, v255, 11
	s_waitcnt lgkmcnt(0)
	v_mul_f32_e32 v33, v121, v33
	v_cndmask_b32_e64 v33, v33, -v33, s[4:5]
	v_fmac_f32_e32 v33, v22, v120
	v_mov_b32_e32 v22, v33
.LBB0_220:
	s_or_b64 exec, exec, s[6:7]
	v_add_u32_e32 v32, 0x110, v32
	s_waitcnt lgkmcnt(0)
	v_cvt_pk_bf16_f32 v33, v22, s0
	v_lshl_add_u32 v22, v64, 1, v32
	ds_write_b16 v22, v33
	ds_bpermute_b32 v33, v70, v23
	s_and_saveexec_b64 s[6:7], vcc
	s_cbranch_execz .LBB0_222
	v_readlane_b32 s36, v255, 4
	v_readlane_b32 s37, v255, 5
	v_cmp_gt_u32_e64 s[4:5], 8, v67
	v_readlane_b32 s38, v255, 6
	v_readlane_b32 s39, v255, 7
	v_readlane_b32 s40, v255, 8
	v_readlane_b32 s41, v255, 9
	v_readlane_b32 s42, v255, 10
	v_readlane_b32 s43, v255, 11
	s_waitcnt lgkmcnt(0)
	v_mul_f32_e32 v33, v123, v33
	v_cndmask_b32_e64 v33, v33, -v33, s[4:5]
	v_fmac_f32_e32 v33, v23, v122
	v_mov_b32_e32 v23, v33
.LBB0_222:
	s_or_b64 exec, exec, s[6:7]
	v_add_u32_e32 v32, 0x110, v32
	s_waitcnt lgkmcnt(0)
	v_cvt_pk_bf16_f32 v33, v23, s0
	v_lshl_add_u32 v23, v64, 1, v32
	ds_write_b16 v23, v33
	ds_bpermute_b32 v33, v70, v24
	s_and_saveexec_b64 s[6:7], vcc
	s_cbranch_execz .LBB0_224
	v_readlane_b32 s36, v255, 4
	v_readlane_b32 s37, v255, 5
	v_cmp_gt_u32_e64 s[4:5], 8, v67
	v_readlane_b32 s38, v255, 6
	v_readlane_b32 s39, v255, 7
	v_readlane_b32 s40, v255, 8
	v_readlane_b32 s41, v255, 9
	v_readlane_b32 s42, v255, 10
	v_readlane_b32 s43, v255, 11
	s_waitcnt lgkmcnt(0)
	v_mul_f32_e32 v33, v125, v33
	v_cndmask_b32_e64 v33, v33, -v33, s[4:5]
	v_fmac_f32_e32 v33, v24, v124
	v_mov_b32_e32 v24, v33
.LBB0_224:
	s_or_b64 exec, exec, s[6:7]
	v_add_u32_e32 v32, 0x550, v32
	s_waitcnt lgkmcnt(0)
	v_cvt_pk_bf16_f32 v33, v24, s0
	v_lshl_add_u32 v24, v64, 1, v32
	ds_write_b16 v24, v33
	ds_bpermute_b32 v33, v70, v25
	s_and_saveexec_b64 s[6:7], vcc
	s_cbranch_execz .LBB0_226
	v_readlane_b32 s36, v255, 4
	v_readlane_b32 s37, v255, 5
	v_cmp_gt_u32_e64 s[4:5], 8, v67
	v_readlane_b32 s38, v255, 6
	v_readlane_b32 s39, v255, 7
	v_readlane_b32 s40, v255, 8
	v_readlane_b32 s41, v255, 9
	v_readlane_b32 s42, v255, 10
	v_readlane_b32 s43, v255, 11
	s_waitcnt lgkmcnt(0)
	v_mul_f32_e32 v33, v127, v33
	v_cndmask_b32_e64 v33, v33, -v33, s[4:5]
	v_fmac_f32_e32 v33, v25, v126
	v_mov_b32_e32 v25, v33
.LBB0_226:
	s_or_b64 exec, exec, s[6:7]
	v_add_u32_e32 v32, 0x110, v32
	s_waitcnt lgkmcnt(0)
	v_cvt_pk_bf16_f32 v33, v25, s0
	v_lshl_add_u32 v25, v64, 1, v32
	ds_write_b16 v25, v33
	ds_bpermute_b32 v33, v70, v26
	s_and_saveexec_b64 s[6:7], vcc
	s_cbranch_execz .LBB0_228
	v_readlane_b32 s36, v255, 4
	v_readlane_b32 s37, v255, 5
	v_cmp_gt_u32_e64 s[4:5], 8, v67
	v_readlane_b32 s38, v255, 6
	v_readlane_b32 s39, v255, 7
	v_readlane_b32 s40, v255, 8
	v_readlane_b32 s41, v255, 9
	v_readlane_b32 s42, v255, 10
	v_readlane_b32 s43, v255, 11
	s_waitcnt vmcnt(0) lgkmcnt(0)
	v_mul_f32_e32 v33, v77, v33
	v_cndmask_b32_e64 v33, v33, -v33, s[4:5]
	v_fmac_f32_e32 v33, v26, v76
	v_mov_b32_e32 v26, v33
.LBB0_228:
	s_or_b64 exec, exec, s[6:7]
	v_add_u32_e32 v32, 0x110, v32
	s_waitcnt lgkmcnt(0)
	v_cvt_pk_bf16_f32 v33, v26, s0
	v_lshl_add_u32 v26, v64, 1, v32
	ds_write_b16 v26, v33
	ds_bpermute_b32 v33, v70, v27
	s_and_saveexec_b64 s[6:7], vcc
	s_cbranch_execz .LBB0_230
	v_readlane_b32 s36, v255, 4
	v_readlane_b32 s37, v255, 5
	v_cmp_gt_u32_e64 s[4:5], 8, v67
	v_readlane_b32 s38, v255, 6
	v_readlane_b32 s39, v255, 7
	v_readlane_b32 s40, v255, 8
	v_readlane_b32 s41, v255, 9
	v_readlane_b32 s42, v255, 10
	v_readlane_b32 s43, v255, 11
	s_waitcnt vmcnt(0) lgkmcnt(0)
	v_mul_f32_e32 v33, v79, v33
	v_cndmask_b32_e64 v33, v33, -v33, s[4:5]
	v_fmac_f32_e32 v33, v27, v78
	v_mov_b32_e32 v27, v33
.LBB0_230:
	s_or_b64 exec, exec, s[6:7]
	v_add_u32_e32 v32, 0x110, v32
	s_waitcnt lgkmcnt(0)
	v_cvt_pk_bf16_f32 v33, v27, s0
	v_lshl_add_u32 v27, v64, 1, v32
	ds_write_b16 v27, v33
	ds_bpermute_b32 v33, v70, v28
	s_and_saveexec_b64 s[6:7], vcc
	s_cbranch_execz .LBB0_232
	v_readlane_b32 s36, v255, 4
	v_readlane_b32 s37, v255, 5
	v_cmp_gt_u32_e64 s[4:5], 8, v67
	v_readlane_b32 s38, v255, 6
	v_readlane_b32 s39, v255, 7
	v_readlane_b32 s40, v255, 8
	v_readlane_b32 s41, v255, 9
	v_readlane_b32 s42, v255, 10
	v_readlane_b32 s43, v255, 11
	s_waitcnt vmcnt(0) lgkmcnt(0)
	v_mul_f32_e32 v33, v81, v33
	v_cndmask_b32_e64 v33, v33, -v33, s[4:5]
	v_fmac_f32_e32 v33, v28, v80
	v_mov_b32_e32 v28, v33
.LBB0_232:
	s_or_b64 exec, exec, s[6:7]
	v_add_u32_e32 v32, 0x550, v32
	s_waitcnt lgkmcnt(0)
	v_cvt_pk_bf16_f32 v33, v28, s0
	v_lshl_add_u32 v28, v64, 1, v32
	ds_write_b16 v28, v33
	ds_bpermute_b32 v33, v70, v29
	s_and_saveexec_b64 s[6:7], vcc
	s_cbranch_execz .LBB0_234
	v_readlane_b32 s36, v255, 4
	v_readlane_b32 s37, v255, 5
	v_cmp_gt_u32_e64 s[4:5], 8, v67
	v_readlane_b32 s38, v255, 6
	v_readlane_b32 s39, v255, 7
	v_readlane_b32 s40, v255, 8
	v_readlane_b32 s41, v255, 9
	v_readlane_b32 s42, v255, 10
	v_readlane_b32 s43, v255, 11
	s_waitcnt vmcnt(0) lgkmcnt(0)
	v_mul_f32_e32 v33, v83, v33
	v_cndmask_b32_e64 v33, v33, -v33, s[4:5]
	v_fmac_f32_e32 v33, v29, v82
	v_mov_b32_e32 v29, v33
.LBB0_234:
	s_or_b64 exec, exec, s[6:7]
	s_waitcnt lgkmcnt(0)
	v_cvt_pk_bf16_f32 v33, v29, s0
	v_add_u32_e32 v29, 0x110, v32
	ds_bpermute_b32 v32, v70, v30
	v_lshl_add_u32 v29, v64, 1, v29
	ds_write_b16 v29, v33
	s_and_saveexec_b64 s[6:7], vcc
	s_cbranch_execz .LBB0_236
	v_readlane_b32 s36, v255, 4
	v_readlane_b32 s37, v255, 5
	v_cmp_gt_u32_e64 s[4:5], 8, v67
	v_readlane_b32 s38, v255, 6
	v_readlane_b32 s39, v255, 7
	v_readlane_b32 s40, v255, 8
	v_readlane_b32 s41, v255, 9
	v_readlane_b32 s42, v255, 10
	v_readlane_b32 s43, v255, 11
	s_waitcnt vmcnt(0) lgkmcnt(0)
	v_mul_f32_e32 v32, v85, v32
	v_cndmask_b32_e64 v32, v32, -v32, s[4:5]
	v_fmac_f32_e32 v32, v30, v84
	v_mov_b32_e32 v30, v32
.LBB0_236:
	s_or_b64 exec, exec, s[6:7]
	s_waitcnt lgkmcnt(0)
	ds_bpermute_b32 v32, v70, v31
	v_cvt_pk_bf16_f32 v30, v30, s0
	ds_write_b16 v29, v30 offset:272
	v_or_b32_e32 v30, 59, v68
	s_and_saveexec_b64 s[4:5], vcc
	s_cbranch_execz .LBB0_238
	v_readlane_b32 s36, v255, 4
	v_readlane_b32 s37, v255, 5
	v_cmp_gt_u32_e32 vcc, 8, v67
	v_readlane_b32 s38, v255, 6
	v_readlane_b32 s39, v255, 7
	v_readlane_b32 s40, v255, 8
	v_readlane_b32 s41, v255, 9
	v_readlane_b32 s42, v255, 10
	v_readlane_b32 s43, v255, 11
	s_waitcnt vmcnt(0) lgkmcnt(0)
	v_mul_f32_e32 v32, v87, v32
	v_cndmask_b32_e64 v32, v32, -v32, vcc
	v_fmac_f32_e32 v32, v31, v86
	v_mov_b32_e32 v31, v32
